# P8 down-proj epilogue rewritten: all 32 residual loads up front + counted vmcnt pipeline (was 32 serial load/wait/store round trips)
# speedup vs baseline: 1.0451x; 1.0074x over previous
.LBB0_939:
	s_add_i32 s20, s40, s38
	s_and_b32 s0, s36, 24
	s_or_b32 s0, s39, s0
	s_lshl_b32 s0, s0, 5
	s_add_i32 s35, s35, 1
	s_add_i32 s24, s24, s25
	s_add_i32 s26, s26, s45
	s_add_i32 s34, s34, s45
	v_and_b32_e32 v130, 15, v238
	v_add_u32_e32 v130, s20, v130
	v_lshrrev_b32_e32 v131, 2, v238
	v_and_b32_e32 v131, 12, v131
	v_lshl_add_u32 v130, v130, 10, v131
	v_add_u32_e32 v130, s0, v130
	v_lshlrev_b32_e32 v132, 1, v130
	v_add_u32_e32 v133, 0x8000, v132
	v_add_u32_e32 v134, 0x10000, v132
	v_add_u32_e32 v135, 0x18000, v132
	v_add_u32_e32 v136, 0x40000, v132
	v_add_u32_e32 v137, 0x48000, v132
	v_add_u32_e32 v138, 0x50000, v132
	v_add_u32_e32 v139, 0x58000, v132
	v_lshlrev_b32_e32 v141, 1, v132
	v_lshlrev_b32_e32 v142, 1, v133
	v_lshlrev_b32_e32 v143, 1, v134
	v_lshlrev_b32_e32 v144, 1, v135
	v_lshlrev_b32_e32 v145, 1, v136
	v_lshlrev_b32_e32 v146, 1, v137
	v_lshlrev_b32_e32 v147, 1, v138
	v_lshlrev_b32_e32 v148, 1, v139
	global_load_dwordx2 v[150:151], v132, s[46:47]
	global_load_dwordx2 v[152:153], v132, s[46:47] offset:32
	global_load_dwordx2 v[154:155], v133, s[46:47]
	global_load_dwordx2 v[156:157], v133, s[46:47] offset:32
	global_load_dwordx2 v[158:159], v134, s[46:47]
	global_load_dwordx2 v[160:161], v134, s[46:47] offset:32
	global_load_dwordx2 v[162:163], v135, s[46:47]
	global_load_dwordx2 v[164:165], v135, s[46:47] offset:32
	global_load_dwordx2 v[166:167], v132, s[46:47] offset:256
	global_load_dwordx2 v[168:169], v132, s[46:47] offset:288
	global_load_dwordx2 v[170:171], v133, s[46:47] offset:256
	global_load_dwordx2 v[172:173], v133, s[46:47] offset:288
	global_load_dwordx2 v[174:175], v134, s[46:47] offset:256
	global_load_dwordx2 v[176:177], v134, s[46:47] offset:288
	global_load_dwordx2 v[178:179], v135, s[46:47] offset:256
	global_load_dwordx2 v[180:181], v135, s[46:47] offset:288
	global_load_dwordx2 v[182:183], v136, s[46:47]
	global_load_dwordx2 v[184:185], v136, s[46:47] offset:32
	global_load_dwordx2 v[186:187], v137, s[46:47]
	global_load_dwordx2 v[188:189], v137, s[46:47] offset:32
	global_load_dwordx2 v[190:191], v138, s[46:47]
	global_load_dwordx2 v[192:193], v138, s[46:47] offset:32
	global_load_dwordx2 v[194:195], v139, s[46:47]
	global_load_dwordx2 v[196:197], v139, s[46:47] offset:32
	global_load_dwordx2 v[198:199], v136, s[46:47] offset:256
	global_load_dwordx2 v[200:201], v136, s[46:47] offset:288
	global_load_dwordx2 v[202:203], v137, s[46:47] offset:256
	global_load_dwordx2 v[204:205], v137, s[46:47] offset:288
	global_load_dwordx2 v[206:207], v138, s[46:47] offset:256
	global_load_dwordx2 v[208:209], v138, s[46:47] offset:288
	global_load_dwordx2 v[210:211], v139, s[46:47] offset:256
	global_load_dwordx2 v[212:213], v139, s[46:47] offset:288
	s_waitcnt vmcnt(31)
	v_lshlrev_b32_e32 v216, 16, v150
	v_and_b32_e32 v217, 0xffff0000, v150
	v_lshlrev_b32_e32 v218, 16, v151
	v_and_b32_e32 v219, 0xffff0000, v151
	v_pk_add_f32 v[124:125], v[124:125], v[216:217]
	v_pk_add_f32 v[126:127], v[126:127], v[218:219]
	global_store_dwordx4 v141, v[124:127], s[58:59]
	s_waitcnt vmcnt(31)
	v_lshlrev_b32_e32 v220, 16, v152
	v_and_b32_e32 v221, 0xffff0000, v152
	v_lshlrev_b32_e32 v222, 16, v153
	v_and_b32_e32 v223, 0xffff0000, v153
	v_pk_add_f32 v[120:121], v[120:121], v[220:221]
	v_pk_add_f32 v[122:123], v[122:123], v[222:223]
	global_store_dwordx4 v141, v[120:123], s[58:59] offset:64
	s_waitcnt vmcnt(31)
	v_lshlrev_b32_e32 v216, 16, v154
	v_and_b32_e32 v217, 0xffff0000, v154
	v_lshlrev_b32_e32 v218, 16, v155
	v_and_b32_e32 v219, 0xffff0000, v155
	v_pk_add_f32 v[116:117], v[116:117], v[216:217]
	v_pk_add_f32 v[118:119], v[118:119], v[218:219]
	global_store_dwordx4 v142, v[116:119], s[58:59]
	s_waitcnt vmcnt(31)
	v_lshlrev_b32_e32 v220, 16, v156
	v_and_b32_e32 v221, 0xffff0000, v156
	v_lshlrev_b32_e32 v222, 16, v157
	v_and_b32_e32 v223, 0xffff0000, v157
	v_pk_add_f32 v[112:113], v[112:113], v[220:221]
	v_pk_add_f32 v[114:115], v[114:115], v[222:223]
	global_store_dwordx4 v142, v[112:115], s[58:59] offset:64
	s_waitcnt vmcnt(31)
	v_lshlrev_b32_e32 v216, 16, v158
	v_and_b32_e32 v217, 0xffff0000, v158
	v_lshlrev_b32_e32 v218, 16, v159
	v_and_b32_e32 v219, 0xffff0000, v159
	v_pk_add_f32 v[108:109], v[108:109], v[216:217]
	v_pk_add_f32 v[110:111], v[110:111], v[218:219]
	global_store_dwordx4 v143, v[108:111], s[58:59]
	s_waitcnt vmcnt(31)
	v_lshlrev_b32_e32 v220, 16, v160
	v_and_b32_e32 v221, 0xffff0000, v160
	v_lshlrev_b32_e32 v222, 16, v161
	v_and_b32_e32 v223, 0xffff0000, v161
	v_pk_add_f32 v[104:105], v[104:105], v[220:221]
	v_pk_add_f32 v[106:107], v[106:107], v[222:223]
	global_store_dwordx4 v143, v[104:107], s[58:59] offset:64
	s_waitcnt vmcnt(31)
	v_lshlrev_b32_e32 v216, 16, v162
	v_and_b32_e32 v217, 0xffff0000, v162
	v_lshlrev_b32_e32 v218, 16, v163
	v_and_b32_e32 v219, 0xffff0000, v163
	v_pk_add_f32 v[100:101], v[100:101], v[216:217]
	v_pk_add_f32 v[102:103], v[102:103], v[218:219]
	global_store_dwordx4 v144, v[100:103], s[58:59]
	s_waitcnt vmcnt(31)
	v_lshlrev_b32_e32 v220, 16, v164
	v_and_b32_e32 v221, 0xffff0000, v164
	v_lshlrev_b32_e32 v222, 16, v165
	v_and_b32_e32 v223, 0xffff0000, v165
	v_pk_add_f32 v[96:97], v[96:97], v[220:221]
	v_pk_add_f32 v[98:99], v[98:99], v[222:223]
	global_store_dwordx4 v144, v[96:99], s[58:59] offset:64
	s_waitcnt vmcnt(31)
	v_lshlrev_b32_e32 v216, 16, v166
	v_and_b32_e32 v217, 0xffff0000, v166
	v_lshlrev_b32_e32 v218, 16, v167
	v_and_b32_e32 v219, 0xffff0000, v167
	v_pk_add_f32 v[92:93], v[92:93], v[216:217]
	v_pk_add_f32 v[94:95], v[94:95], v[218:219]
	global_store_dwordx4 v141, v[92:95], s[58:59] offset:512
	s_waitcnt vmcnt(31)
	v_lshlrev_b32_e32 v220, 16, v168
	v_and_b32_e32 v221, 0xffff0000, v168
	v_lshlrev_b32_e32 v222, 16, v169
	v_and_b32_e32 v223, 0xffff0000, v169
	v_pk_add_f32 v[88:89], v[88:89], v[220:221]
	v_pk_add_f32 v[90:91], v[90:91], v[222:223]
	global_store_dwordx4 v141, v[88:91], s[58:59] offset:576
	s_waitcnt vmcnt(31)
	v_lshlrev_b32_e32 v216, 16, v170
	v_and_b32_e32 v217, 0xffff0000, v170
	v_lshlrev_b32_e32 v218, 16, v171
	v_and_b32_e32 v219, 0xffff0000, v171
	v_pk_add_f32 v[84:85], v[84:85], v[216:217]
	v_pk_add_f32 v[86:87], v[86:87], v[218:219]
	global_store_dwordx4 v142, v[84:87], s[58:59] offset:512
	s_waitcnt vmcnt(31)
	v_lshlrev_b32_e32 v220, 16, v172
	v_and_b32_e32 v221, 0xffff0000, v172
	v_lshlrev_b32_e32 v222, 16, v173
	v_and_b32_e32 v223, 0xffff0000, v173
	v_pk_add_f32 v[80:81], v[80:81], v[220:221]
	v_pk_add_f32 v[82:83], v[82:83], v[222:223]
	global_store_dwordx4 v142, v[80:83], s[58:59] offset:576
	s_waitcnt vmcnt(31)
	v_lshlrev_b32_e32 v216, 16, v174
	v_and_b32_e32 v217, 0xffff0000, v174
	v_lshlrev_b32_e32 v218, 16, v175
	v_and_b32_e32 v219, 0xffff0000, v175
	v_pk_add_f32 v[76:77], v[76:77], v[216:217]
	v_pk_add_f32 v[78:79], v[78:79], v[218:219]
	global_store_dwordx4 v143, v[76:79], s[58:59] offset:512
	s_waitcnt vmcnt(31)
	v_lshlrev_b32_e32 v220, 16, v176
	v_and_b32_e32 v221, 0xffff0000, v176
	v_lshlrev_b32_e32 v222, 16, v177
	v_and_b32_e32 v223, 0xffff0000, v177
	v_pk_add_f32 v[72:73], v[72:73], v[220:221]
	v_pk_add_f32 v[74:75], v[74:75], v[222:223]
	global_store_dwordx4 v143, v[72:75], s[58:59] offset:576
	s_waitcnt vmcnt(31)
	v_lshlrev_b32_e32 v216, 16, v178
	v_and_b32_e32 v217, 0xffff0000, v178
	v_lshlrev_b32_e32 v218, 16, v179
	v_and_b32_e32 v219, 0xffff0000, v179
	v_pk_add_f32 v[68:69], v[68:69], v[216:217]
	v_pk_add_f32 v[70:71], v[70:71], v[218:219]
	global_store_dwordx4 v144, v[68:71], s[58:59] offset:512
	s_waitcnt vmcnt(31)
	v_lshlrev_b32_e32 v220, 16, v180
	v_and_b32_e32 v221, 0xffff0000, v180
	v_lshlrev_b32_e32 v222, 16, v181
	v_and_b32_e32 v223, 0xffff0000, v181
	v_pk_add_f32 v[64:65], v[64:65], v[220:221]
	v_pk_add_f32 v[66:67], v[66:67], v[222:223]
	global_store_dwordx4 v144, v[64:67], s[58:59] offset:576
	s_waitcnt vmcnt(31)
	v_lshlrev_b32_e32 v216, 16, v182
	v_and_b32_e32 v217, 0xffff0000, v182
	v_lshlrev_b32_e32 v218, 16, v183
	v_and_b32_e32 v219, 0xffff0000, v183
	v_pk_add_f32 v[60:61], v[60:61], v[216:217]
	v_pk_add_f32 v[62:63], v[62:63], v[218:219]
	global_store_dwordx4 v145, v[60:63], s[58:59]
	s_waitcnt vmcnt(31)
	v_lshlrev_b32_e32 v220, 16, v184
	v_and_b32_e32 v221, 0xffff0000, v184
	v_lshlrev_b32_e32 v222, 16, v185
	v_and_b32_e32 v223, 0xffff0000, v185
	v_pk_add_f32 v[56:57], v[56:57], v[220:221]
	v_pk_add_f32 v[58:59], v[58:59], v[222:223]
	global_store_dwordx4 v145, v[56:59], s[58:59] offset:64
	s_waitcnt vmcnt(31)
	v_lshlrev_b32_e32 v216, 16, v186
	v_and_b32_e32 v217, 0xffff0000, v186
	v_lshlrev_b32_e32 v218, 16, v187
	v_and_b32_e32 v219, 0xffff0000, v187
	v_pk_add_f32 v[52:53], v[52:53], v[216:217]
	v_pk_add_f32 v[54:55], v[54:55], v[218:219]
	global_store_dwordx4 v146, v[52:55], s[58:59]
	s_waitcnt vmcnt(31)
	v_lshlrev_b32_e32 v220, 16, v188
	v_and_b32_e32 v221, 0xffff0000, v188
	v_lshlrev_b32_e32 v222, 16, v189
	v_and_b32_e32 v223, 0xffff0000, v189
	v_pk_add_f32 v[48:49], v[48:49], v[220:221]
	v_pk_add_f32 v[50:51], v[50:51], v[222:223]
	global_store_dwordx4 v146, v[48:51], s[58:59] offset:64
	s_waitcnt vmcnt(31)
	v_lshlrev_b32_e32 v216, 16, v190
	v_and_b32_e32 v217, 0xffff0000, v190
	v_lshlrev_b32_e32 v218, 16, v191
	v_and_b32_e32 v219, 0xffff0000, v191
	v_pk_add_f32 v[44:45], v[44:45], v[216:217]
	v_pk_add_f32 v[46:47], v[46:47], v[218:219]
	global_store_dwordx4 v147, v[44:47], s[58:59]
	s_waitcnt vmcnt(31)
	v_lshlrev_b32_e32 v220, 16, v192
	v_and_b32_e32 v221, 0xffff0000, v192
	v_lshlrev_b32_e32 v222, 16, v193
	v_and_b32_e32 v223, 0xffff0000, v193
	v_pk_add_f32 v[40:41], v[40:41], v[220:221]
	v_pk_add_f32 v[42:43], v[42:43], v[222:223]
	global_store_dwordx4 v147, v[40:43], s[58:59] offset:64
	s_waitcnt vmcnt(31)
	v_lshlrev_b32_e32 v216, 16, v194
	v_and_b32_e32 v217, 0xffff0000, v194
	v_lshlrev_b32_e32 v218, 16, v195
	v_and_b32_e32 v219, 0xffff0000, v195
	v_pk_add_f32 v[36:37], v[36:37], v[216:217]
	v_pk_add_f32 v[38:39], v[38:39], v[218:219]
	global_store_dwordx4 v148, v[36:39], s[58:59]
	s_waitcnt vmcnt(31)
	v_lshlrev_b32_e32 v220, 16, v196
	v_and_b32_e32 v221, 0xffff0000, v196
	v_lshlrev_b32_e32 v222, 16, v197
	v_and_b32_e32 v223, 0xffff0000, v197
	v_pk_add_f32 v[32:33], v[32:33], v[220:221]
	v_pk_add_f32 v[34:35], v[34:35], v[222:223]
	global_store_dwordx4 v148, v[32:35], s[58:59] offset:64
	s_waitcnt vmcnt(31)
	v_lshlrev_b32_e32 v216, 16, v198
	v_and_b32_e32 v217, 0xffff0000, v198
	v_lshlrev_b32_e32 v218, 16, v199
	v_and_b32_e32 v219, 0xffff0000, v199
	v_pk_add_f32 v[28:29], v[28:29], v[216:217]
	v_pk_add_f32 v[30:31], v[30:31], v[218:219]
	global_store_dwordx4 v145, v[28:31], s[58:59] offset:512
	s_waitcnt vmcnt(31)
	v_lshlrev_b32_e32 v220, 16, v200
	v_and_b32_e32 v221, 0xffff0000, v200
	v_lshlrev_b32_e32 v222, 16, v201
	v_and_b32_e32 v223, 0xffff0000, v201
	v_pk_add_f32 v[24:25], v[24:25], v[220:221]
	v_pk_add_f32 v[26:27], v[26:27], v[222:223]
	global_store_dwordx4 v145, v[24:27], s[58:59] offset:576
	s_waitcnt vmcnt(31)
	v_lshlrev_b32_e32 v216, 16, v202
	v_and_b32_e32 v217, 0xffff0000, v202
	v_lshlrev_b32_e32 v218, 16, v203
	v_and_b32_e32 v219, 0xffff0000, v203
	v_pk_add_f32 v[20:21], v[20:21], v[216:217]
	v_pk_add_f32 v[22:23], v[22:23], v[218:219]
	global_store_dwordx4 v146, v[20:23], s[58:59] offset:512
	s_waitcnt vmcnt(31)
	v_lshlrev_b32_e32 v220, 16, v204
	v_and_b32_e32 v221, 0xffff0000, v204
	v_lshlrev_b32_e32 v222, 16, v205
	v_and_b32_e32 v223, 0xffff0000, v205
	v_pk_add_f32 v[16:17], v[16:17], v[220:221]
	v_pk_add_f32 v[18:19], v[18:19], v[222:223]
	global_store_dwordx4 v146, v[16:19], s[58:59] offset:576
	s_waitcnt vmcnt(31)
	v_lshlrev_b32_e32 v216, 16, v206
	v_and_b32_e32 v217, 0xffff0000, v206
	v_lshlrev_b32_e32 v218, 16, v207
	v_and_b32_e32 v219, 0xffff0000, v207
	v_pk_add_f32 v[12:13], v[12:13], v[216:217]
	v_pk_add_f32 v[14:15], v[14:15], v[218:219]
	global_store_dwordx4 v147, v[12:15], s[58:59] offset:512
	s_waitcnt vmcnt(31)
	v_lshlrev_b32_e32 v220, 16, v208
	v_and_b32_e32 v221, 0xffff0000, v208
	v_lshlrev_b32_e32 v222, 16, v209
	v_and_b32_e32 v223, 0xffff0000, v209
	v_pk_add_f32 v[8:9], v[8:9], v[220:221]
	v_pk_add_f32 v[10:11], v[10:11], v[222:223]
	global_store_dwordx4 v147, v[8:11], s[58:59] offset:576
	s_waitcnt vmcnt(31)
	v_lshlrev_b32_e32 v216, 16, v210
	v_and_b32_e32 v217, 0xffff0000, v210
	v_lshlrev_b32_e32 v218, 16, v211
	v_and_b32_e32 v219, 0xffff0000, v211
	v_pk_add_f32 v[4:5], v[4:5], v[216:217]
	v_pk_add_f32 v[6:7], v[6:7], v[218:219]
	global_store_dwordx4 v148, v[4:7], s[58:59] offset:512
	s_waitcnt vmcnt(31)
	v_lshlrev_b32_e32 v220, 16, v212
	v_and_b32_e32 v221, 0xffff0000, v212
	v_lshlrev_b32_e32 v222, 16, v213
	v_and_b32_e32 v223, 0xffff0000, v213
	v_pk_add_f32 v[0:1], v[0:1], v[220:221]
	v_pk_add_f32 v[2:3], v[2:3], v[222:223]
	global_store_dwordx4 v148, v[0:3], s[58:59] offset:576
	s_mul_i32 s0, s35, s45
	s_add_i32 s36, s0, s83
	s_cmp_lt_u32 s36, 64
	s_cbranch_scc0 .LBB0_946
